# P4 rope tiles: cos/sin of the next row-group prefetched one row ahead (no per-row vmcnt(0) drain)
# speedup vs baseline: 1.0066x; 1.0029x over previous
; #define PG8_LAS __attribute__((address_space(3)))
; #define EPI_ROWS _Pragma("unroll") for (int ai = 0; ai < 2; ++ai) _Pragma("unroll") for (int m = 0; m < 4; ++m)
; __device__ __forceinline__ float rstd_lds(const PG8_LAS unsigned char* scr, int lrow) {
;     const PG8_LAS f32x4* p = (const PG8_LAS f32x4*)(scr + lrow * 64);
;     const f32x4 s = (p[0] + p[1]) + (p[2] + p[3]);
;     return __builtin_amdgcn_rsqf(((s[0] + s[1]) + (s[2] + s[3])) * (1.0f / DM) + RMS_EPS);
; }
;     __device__ __forceinline__ void operator()(const f32x4 (&acc)[2][2][4][2], const Unit& u, int wr, int wc, int fr, int fq) const {
;     ...
;         EPI_ROWS { rsv[ai][m] = rstd_lds(scr, EPI_LROW); asm volatile("" : "+v"(rsv[ai][m]) :: "memory"); }
.LBB0_462:
	v_lshlrev_b32_e32 v165, 6, v175
	v_add_u32_e32 v146, s89, v165
	ds_read_b128 v[148:151], v146
	ds_read_b128 v[152:155], v146 offset:16
	ds_read_b128 v[156:159], v146 offset:32
	ds_read_b128 v[160:163], v146 offset:48
	v_lshlrev_b32_e32 v197, 4, v147
	v_add_u32_e32 v147, v197, v175
	v_add_u32_e32 v228, s90, v165
	ds_read_b128 v[230:233], v228
	ds_read_b128 v[234:237], v228 offset:16
	ds_read_b128 v[238:241], v228 offset:32
	ds_read_b128 v[242:245], v228 offset:48
	s_waitcnt lgkmcnt(4)
	v_pk_add_f32 v[150:151], v[150:151], v[154:155]
	v_pk_add_f32 v[148:149], v[148:149], v[152:153]
	v_pk_add_f32 v[152:153], v[158:159], v[162:163]
	v_pk_add_f32 v[154:155], v[156:157], v[160:161]
	v_pk_add_f32 v[150:151], v[150:151], v[152:153]
	v_pk_add_f32 v[148:149], v[148:149], v[154:155]
	v_pk_mov_b32 v[152:153], v[148:149], v[150:151] op_sel:[1,0]
	v_mov_b32_e32 v149, v151
	v_pk_add_f32 v[148:149], v[152:153], v[148:149]
	v_lshlrev_b32_e32 v177, 4, v147
	v_add_f32_e32 v146, v148, v149
	v_fmamk_f32 v146, v146, 0x3a800000, v211
	v_rsq_f32_e32 v146, v146
	v_ashrrev_i32_e32 v147, 3, v147
	s_lshl_b32 s31, s4, 8
	v_add_u32_e32 v228, s91, v165
	ds_read_b128 v[148:151], v228
	ds_read_b128 v[152:155], v228 offset:16
	ds_read_b128 v[156:159], v228 offset:32
	ds_read_b128 v[160:163], v228 offset:48
	s_waitcnt lgkmcnt(4)
	v_pk_add_f32 v[232:233], v[232:233], v[236:237]
	v_pk_add_f32 v[230:231], v[230:231], v[234:235]
	v_pk_add_f32 v[234:235], v[240:241], v[244:245]
	v_pk_add_f32 v[236:237], v[238:239], v[242:243]
	v_pk_add_f32 v[232:233], v[232:233], v[234:235]
	v_pk_add_f32 v[230:231], v[230:231], v[236:237]
	v_add_f32_e32 v230, v230, v231
	v_add_f32_e32 v231, v232, v233
	v_add_f32_e32 v230, v230, v231
	v_fmamk_f32 v230, v230, 0x3a800000, v211
	v_rsq_f32_e32 v206, v230
	v_mad_u64_u32 v[172:173], s[4:5], s52, v147, 0
	v_add_u32_e32 v228, s92, v165
	ds_read_b128 v[230:233], v228
	ds_read_b128 v[234:237], v228 offset:16
	ds_read_b128 v[238:241], v228 offset:32
	ds_read_b128 v[242:245], v228 offset:48
	s_waitcnt lgkmcnt(4)
	v_pk_add_f32 v[150:151], v[150:151], v[154:155]
	v_pk_add_f32 v[148:149], v[148:149], v[152:153]
	v_pk_add_f32 v[152:153], v[158:159], v[162:163]
	v_pk_add_f32 v[154:155], v[156:157], v[160:161]
	v_pk_add_f32 v[150:151], v[150:151], v[152:153]
	v_pk_add_f32 v[148:149], v[148:149], v[154:155]
	v_add_f32_e32 v148, v148, v149
	v_add_f32_e32 v149, v150, v151
	v_add_f32_e32 v148, v148, v149
	v_fmamk_f32 v148, v148, 0x3a800000, v211
	v_rsq_f32_e32 v202, v148
	s_add_i32 s8, s84, s8
	s_ashr_i32 s9, s8, 31
	v_add_u32_e32 v228, s93, v165
	ds_read_b128 v[148:151], v228
	ds_read_b128 v[152:155], v228 offset:16
	ds_read_b128 v[156:159], v228 offset:32
	ds_read_b128 v[160:163], v228 offset:48
	s_waitcnt lgkmcnt(4)
	v_pk_add_f32 v[232:233], v[232:233], v[236:237]
	v_pk_add_f32 v[230:231], v[230:231], v[234:235]
	v_pk_add_f32 v[234:235], v[240:241], v[244:245]
	v_pk_add_f32 v[236:237], v[238:239], v[242:243]
	v_pk_add_f32 v[232:233], v[232:233], v[234:235]
	v_pk_add_f32 v[230:231], v[230:231], v[236:237]
	v_add_f32_e32 v230, v230, v231
	v_add_f32_e32 v231, v232, v233
	v_add_f32_e32 v230, v230, v231
	v_fmamk_f32 v230, v230, 0x3a800000, v211
	v_rsq_f32_e32 v200, v230
	s_xor_b64 s[56:57], s[56:57], -1
	s_add_i32 s31, s31, s79
	v_add_u32_e32 v228, s94, v165
	ds_read_b128 v[230:233], v228
	ds_read_b128 v[234:237], v228 offset:16
	ds_read_b128 v[238:241], v228 offset:32
	ds_read_b128 v[242:245], v228 offset:48
	s_waitcnt lgkmcnt(4)
	v_pk_add_f32 v[150:151], v[150:151], v[154:155]
	v_pk_add_f32 v[148:149], v[148:149], v[152:153]
	v_pk_add_f32 v[152:153], v[158:159], v[162:163]
	v_pk_add_f32 v[154:155], v[156:157], v[160:161]
	v_pk_add_f32 v[150:151], v[150:151], v[152:153]
	v_pk_add_f32 v[148:149], v[148:149], v[154:155]
	v_add_f32_e32 v148, v148, v149
	v_add_f32_e32 v149, v150, v151
	v_add_f32_e32 v148, v148, v149
	v_fmamk_f32 v148, v148, 0x3a800000, v211
	v_rsq_f32_e32 v198, v148
	s_mov_b64 s[60:61], -1
	s_xor_b64 s[58:59], s[58:59], -1
	v_add_u32_e32 v228, s95, v165
	ds_read_b128 v[148:151], v228
	ds_read_b128 v[152:155], v228 offset:16
	ds_read_b128 v[156:159], v228 offset:32
	ds_read_b128 v[160:163], v228 offset:48
	s_waitcnt lgkmcnt(4)
	v_pk_add_f32 v[232:233], v[232:233], v[236:237]
	v_pk_add_f32 v[230:231], v[230:231], v[234:235]
	v_pk_add_f32 v[234:235], v[240:241], v[244:245]
	v_pk_add_f32 v[236:237], v[238:239], v[242:243]
	v_pk_add_f32 v[232:233], v[232:233], v[234:235]
	v_pk_add_f32 v[230:231], v[230:231], v[236:237]
	v_add_f32_e32 v230, v230, v231
	v_add_f32_e32 v231, v232, v233
	v_add_f32_e32 v230, v230, v231
	v_fmamk_f32 v230, v230, 0x3a800000, v211
	v_rsq_f32_e32 v196, v230
	v_cmp_gt_u32_e64 s[6:7], 8, v175
	v_add_u32_e32 v212, s31, v175
	v_add_u32_e32 v228, s96, v165
	ds_read_b128 v[230:233], v228
	ds_read_b128 v[234:237], v228 offset:16
	ds_read_b128 v[238:241], v228 offset:32
	ds_read_b128 v[242:245], v228 offset:48
	s_waitcnt lgkmcnt(4)
; __device__ __forceinline__ u32x4 pack8(const f32x4 a, const f32x4 b) { u32x4 w; w.x = cvt_pk_bf16(a[0], a[1]); w.y = cvt_pk_bf16(a[2], a[3]); w.z = cvt_pk_bf16(b[0], b[1]); w.w = cvt_pk_bf16(b[2], b[3]); return w; }
; #define ROPE_LOAD(C0, C1, S0, S1, r_) do { const int pos_ = (u.pm * BM + ((r_) >> 2) * HALF + wr * 64 + ((r_) & 3) * 16 + fr) & (SEQ - 1); const float* cp_ = cosT + pos_ * 32 + fq * 8; const float* sp_ = sinT + pos_ * 32 + fq * 8; \
;             C0 = *(const f32x4*)cp_; C1 = *(const f32x4*)(cp_ + 4); S0 = *(const f32x4*)sp_; S1 = *(const f32x4*)(sp_ + 4); } while (0)
;     __device__ __forceinline__ void operator()(const f32x4 (&acc)[2][2][4][2], const Unit& u, int wr, int wc, int fr, int fq) const {
;     ...
; #pragma unroll
;         for (int r = 0; r < 8; ++r) { const int ai = r >> 2, m = r & 3; const int row = EPI_ROW; const float rs = rsv[ai][m];
;             f32x4 a0 = acc[ai][0][m][0] * rs + ba0, a1 = acc[ai][0][m][1] * rs + ba1, b0 = acc[ai][1][m][0] * rs + bb0, b1 = acc[ai][1][m][1] * rs + bb1;
;             bf16_t* rp = dst + (size_t)row * pitch;
;             if (mode == 1) { *(u32x4*)(rp + c0) = pack8(a0 * b0, a1 * b1); }
;             else if (mode == 3) {
; #pragma unroll
;                 for (int i = 0; i < 4; ++i) {
;                     const float ea0 = __expf(-a0[i]), ea1 = __expf(-a1[i]), eb0 = __expf(-b0[i]), eb1 = __expf(-b1[i]);
;                     a0[i] = (1.f + eb0) * __builtin_amdgcn_rcpf(1.f + ea0); a1[i] = (1.f + eb1) * __builtin_amdgcn_rcpf(1.f + ea1); b0[i] = __builtin_amdgcn_rcpf(1.f + eb0); b1[i] = __builtin_amdgcn_rcpf(1.f + eb1); }
;                 { const size_t po = (size_t)(row >> 1) * (2 * DM) + ((pn - 18) * 4 + wc) * 64 + (row & 1) * 32 + fq * 8;
;                   *(u32x4*)(SZC + po) = pack8(a0, a1); *(u32x4*)(SZA + po) = pack8(b0, b1); } }
;             else {
;                 if (mode == 2) { f32x4 cA, cB, sA, sB; ROPE_LOAD(cA, cB, sA, sB, r); const f32x4 x0 = a0, x1 = a1, y0 = b0, y1 = b1;
;                     a0 = x0 * cA - y0 * sA; a1 = x1 * cB - y1 * sB; b0 = y0 * cA + x0 * sA; b1 = y1 * cB + x1 * sB; }
	v_pk_add_f32 v[150:151], v[150:151], v[154:155]
	v_pk_add_f32 v[148:149], v[148:149], v[152:153]
	v_pk_add_f32 v[152:153], v[158:159], v[162:163]
	v_pk_add_f32 v[154:155], v[156:157], v[160:161]
	v_pk_add_f32 v[150:151], v[150:151], v[152:153]
	v_pk_add_f32 v[148:149], v[148:149], v[154:155]
	v_add_f32_e32 v148, v148, v149
	v_add_f32_e32 v149, v150, v151
	v_add_f32_e32 v148, v148, v149
	v_fmamk_f32 v148, v148, 0x3a800000, v211
	v_rsq_f32_e32 v176, v148
	v_ashrrev_i32_e32 v165, 31, v164
	s_and_b64 vcc, exec, s[56:57]
	s_waitcnt lgkmcnt(0)
	v_pk_add_f32 v[232:233], v[232:233], v[236:237]
	v_pk_add_f32 v[230:231], v[230:231], v[234:235]
	v_pk_add_f32 v[234:235], v[240:241], v[244:245]
	v_pk_add_f32 v[236:237], v[238:239], v[242:243]
	v_pk_add_f32 v[232:233], v[232:233], v[234:235]
	v_pk_add_f32 v[230:231], v[230:231], v[236:237]
	s_nop 0
	v_add_f32_e32 v230, v230, v231
	v_add_f32_e32 v231, v232, v233
	v_add_f32_e32 v230, v230, v231
	v_fmamk_f32 v230, v230, 0x3a800000, v211
	v_rsq_f32_e32 v174, v230
	v_sub_u32_e32 v148, v204, v164
	v_lshlrev_b32_e32 v150, 7, v175
	v_ashrrev_i32_e32 v149, 31, v148
	v_and_b32_e32 v199, 0x380, v150
	v_lshlrev_b32_e32 v150, 4, v175
	v_lshl_add_u64 v[148:149], v[148:149], 1, s[10:11]
	v_and_b32_e32 v186, 0x70, v150
	v_lshl_add_u64 v[170:171], v[148:149], 0, v[186:187]
	v_ashrrev_i32_e32 v148, 31, v147
	v_mul_lo_u32 v148, s52, v148
	v_mul_lo_u32 v149, s53, v147
	v_add3_u32 v173, v173, v148, v149
	v_and_b32_e32 v148, -8, v175
	v_add_u32_e32 v147, 8, v147
	v_cmp_eq_u32_e64 s[4:5], 8, v148
	v_ashrrev_i32_e32 v148, 31, v147
	v_mul_lo_u32 v148, s52, v148
	v_mul_lo_u32 v149, s53, v147
	v_mad_u64_u32 v[168:169], s[28:29], s52, v147, 0
	v_lshlrev_b32_e32 v147, 5, v175
	v_add3_u32 v169, v169, v148, v149
	v_and_b32_e32 v186, 32, v147
	v_lshl_add_u64 v[148:149], v[164:165], 0, s[8:9]
	v_lshl_add_u64 v[166:167], v[148:149], 0, v[186:187]
	v_pk_fma_f32 v[144:145], v[144:145], v[146:147], v[56:57] op_sel_hi:[1,0,1]
	v_pk_fma_f32 v[142:143], v[142:143], v[146:147], v[54:55] op_sel_hi:[1,0,1]
	v_pk_fma_f32 v[140:141], v[140:141], v[146:147], v[52:53] op_sel_hi:[1,0,1]
	v_pk_fma_f32 v[138:139], v[138:139], v[146:147], v[50:51] op_sel_hi:[1,0,1]
	v_pk_fma_f32 v[136:137], v[136:137], v[146:147], v[48:49] op_sel_hi:[1,0,1]
	v_pk_fma_f32 v[134:135], v[134:135], v[146:147], v[46:47] op_sel_hi:[1,0,1]
	v_pk_fma_f32 v[132:133], v[132:133], v[146:147], v[44:45] op_sel_hi:[1,0,1]
	v_pk_fma_f32 v[130:131], v[130:131], v[146:147], v[42:43] op_sel_hi:[1,0,1]
	s_cbranch_vccz .LBB0_474
	s_mov_b64 s[8:9], -1
	s_and_b64 vcc, exec, s[58:59]
	s_cbranch_vccz .LBB0_471
	v_mov_b64_e32 v[154:155], v[132:133]
	v_mov_b64_e32 v[158:159], v[136:137]
	v_mov_b64_e32 v[150:151], v[140:141]
	v_mov_b64_e32 v[162:163], v[144:145]
	s_andn2_b64 vcc, exec, s[54:55]
	v_mov_b64_e32 v[152:153], v[130:131]
	v_mov_b64_e32 v[156:157], v[134:135]
	v_mov_b64_e32 v[148:149], v[138:139]
	v_mov_b64_e32 v[160:161], v[142:143]
	s_cbranch_vccnz .LBB0_466
	s_mov_b64 s[98:99], 0x800
	s_mov_b64 s[100:101], 0x2800
	v_lshlrev_b32_e32 v146, 7, v212
	v_and_b32_e32 v186, 0xfff80, v146
	v_lshlrev_b64 v[154:155], 2, v[164:165]
	v_lshl_add_u64 v[146:147], s[20:21], 0, v[186:187]
	v_lshl_add_u64 v[150:151], v[146:147], 0, v[154:155]
	v_mov_b64_e32 v[246:247], v[150:151]
	v_lshl_add_u64 v[156:157], s[18:19], 0, v[186:187]
	global_load_dwordx4 v[146:149], v[150:151], off
	s_nop 0
	global_load_dwordx4 v[150:153], v[150:151], off offset:16
	v_lshl_add_u64 v[158:159], v[156:157], 0, v[154:155]
	v_mov_b64_e32 v[248:249], v[158:159]
	global_load_dwordx4 v[154:157], v[158:159], off
	global_load_dwordx4 v[214:217], v[158:159], off offset:16
	v_lshl_add_u64 v[246:247], v[246:247], 0, s[98:99]
	v_lshl_add_u64 v[248:249], v[248:249], 0, s[98:99]
	global_load_dwordx4 v[230:233], v[246:247], off
	global_load_dwordx4 v[234:237], v[246:247], off offset:16
	global_load_dwordx4 v[238:241], v[248:249], off
	global_load_dwordx4 v[242:245], v[248:249], off offset:16
	s_waitcnt vmcnt(4)
	v_pk_mul_f32 v[158:159], v[136:137], v[148:149]
	v_pk_mul_f32 v[160:161], v[134:135], v[146:147]
	v_pk_mul_f32 v[218:219], v[132:133], v[152:153]
	v_pk_mul_f32 v[222:223], v[130:131], v[150:151]
	v_pk_mul_f32 v[224:225], v[144:145], v[148:149]
	v_pk_mul_f32 v[146:147], v[142:143], v[146:147]
	v_pk_mul_f32 v[152:153], v[140:141], v[152:153]
	v_pk_mul_f32 v[226:227], v[138:139], v[150:151]
	v_pk_fma_f32 v[162:163], v[144:145], v[156:157], v[158:159] neg_lo:[0,0,1] neg_hi:[0,0,1]
	v_pk_fma_f32 v[160:161], v[142:143], v[154:155], v[160:161] neg_lo:[0,0,1] neg_hi:[0,0,1]
	v_pk_fma_f32 v[150:151], v[140:141], v[216:217], v[218:219] neg_lo:[0,0,1] neg_hi:[0,0,1]
	v_pk_fma_f32 v[148:149], v[138:139], v[214:215], v[222:223] neg_lo:[0,0,1] neg_hi:[0,0,1]
	v_pk_fma_f32 v[158:159], v[136:137], v[156:157], v[224:225]
	v_pk_fma_f32 v[156:157], v[134:135], v[154:155], v[146:147]
	v_pk_fma_f32 v[154:155], v[132:133], v[216:217], v[152:153]
	v_pk_fma_f32 v[152:153], v[130:131], v[214:215], v[226:227]

; __device__ __forceinline__ u32x4 pack8(const f32x4 a, const f32x4 b) { u32x4 w; w.x = cvt_pk_bf16(a[0], a[1]); w.y = cvt_pk_bf16(a[2], a[3]); w.z = cvt_pk_bf16(b[0], b[1]); w.w = cvt_pk_bf16(b[2], b[3]); return w; }
; #define ROPE_LOAD(C0, C1, S0, S1, r_) do { const int pos_ = (u.pm * BM + ((r_) >> 2) * HALF + wr * 64 + ((r_) & 3) * 16 + fr) & (SEQ - 1); const float* cp_ = cosT + pos_ * 32 + fq * 8; const float* sp_ = sinT + pos_ * 32 + fq * 8; \
;             C0 = *(const f32x4*)cp_; C1 = *(const f32x4*)(cp_ + 4); S0 = *(const f32x4*)sp_; S1 = *(const f32x4*)(sp_ + 4); } while (0)
;     __device__ __forceinline__ void operator()(const f32x4 (&acc)[2][2][4][2], const Unit& u, int wr, int wc, int fr, int fq) const {
;     ...
; #pragma unroll
;         for (int r = 0; r < 8; ++r) { const int ai = r >> 2, m = r & 3; const int row = EPI_ROW; const float rs = rsv[ai][m];
;             f32x4 a0 = acc[ai][0][m][0] * rs + ba0, a1 = acc[ai][0][m][1] * rs + ba1, b0 = acc[ai][1][m][0] * rs + bb0, b1 = acc[ai][1][m][1] * rs + bb1;
;             bf16_t* rp = dst + (size_t)row * pitch;
;             if (mode == 1) { *(u32x4*)(rp + c0) = pack8(a0 * b0, a1 * b1); }
;             else if (mode == 3) {
; #pragma unroll
;                 for (int i = 0; i < 4; ++i) {
;                     const float ea0 = __expf(-a0[i]), ea1 = __expf(-a1[i]), eb0 = __expf(-b0[i]), eb1 = __expf(-b1[i]);
;                     a0[i] = (1.f + eb0) * __builtin_amdgcn_rcpf(1.f + ea0); a1[i] = (1.f + eb1) * __builtin_amdgcn_rcpf(1.f + ea1); b0[i] = __builtin_amdgcn_rcpf(1.f + eb0); b1[i] = __builtin_amdgcn_rcpf(1.f + eb1); }
;                 { const size_t po = (size_t)(row >> 1) * (2 * DM) + ((pn - 18) * 4 + wc) * 64 + (row & 1) * 32 + fq * 8;
;                   *(u32x4*)(SZC + po) = pack8(a0, a1); *(u32x4*)(SZA + po) = pack8(b0, b1); } }
;             else {
;                 if (mode == 2) { f32x4 cA, cB, sA, sB; ROPE_LOAD(cA, cB, sA, sB, r); const f32x4 x0 = a0, x1 = a1, y0 = b0, y1 = b1;
;                     a0 = x0 * cA - y0 * sA; a1 = x1 * cB - y1 * sB; b0 = y0 * cA + x0 * sA; b1 = y1 * cB + x1 * sB; }
.LBB0_476:
	s_nop 1
	v_cndmask_b32_e64 v130, 0, 1, s[56:57]
	s_or_b32 s28, s31, 16
	v_cmp_ne_u32_e64 s[10:11], 1, v130
	v_cndmask_b32_e64 v130, 0, 1, s[58:59]
	v_add_u32_e32 v150, s28, v175
	v_pk_fma_f32 v[128:129], v[128:129], v[206:207], v[56:57] op_sel_hi:[1,0,1]
	v_pk_fma_f32 v[126:127], v[126:127], v[206:207], v[54:55] op_sel_hi:[1,0,1]
	v_pk_fma_f32 v[124:125], v[124:125], v[206:207], v[52:53] op_sel_hi:[1,0,1]
	v_pk_fma_f32 v[122:123], v[122:123], v[206:207], v[50:51] op_sel_hi:[1,0,1]
	v_pk_fma_f32 v[120:121], v[120:121], v[206:207], v[48:49] op_sel_hi:[1,0,1]
	v_pk_fma_f32 v[118:119], v[118:119], v[206:207], v[46:47] op_sel_hi:[1,0,1]
	v_pk_fma_f32 v[116:117], v[116:117], v[206:207], v[44:45] op_sel_hi:[1,0,1]
	v_pk_fma_f32 v[114:115], v[114:115], v[206:207], v[42:43] op_sel_hi:[1,0,1]
	s_mov_b64 s[60:61], -1
	s_andn2_b64 vcc, exec, s[56:57]
	v_cmp_ne_u32_e64 s[8:9], 1, v130
	s_cbranch_vccnz .LBB0_488
	s_and_b64 vcc, exec, s[8:9]
	s_mov_b64 s[56:57], -1
	s_cbranch_vccnz .LBB0_485
	v_mov_b64_e32 v[138:139], v[116:117]
	v_mov_b64_e32 v[142:143], v[120:121]
	v_mov_b64_e32 v[134:135], v[124:125]
	v_mov_b64_e32 v[146:147], v[128:129]
	s_andn2_b64 vcc, exec, s[54:55]
	v_mov_b64_e32 v[136:137], v[114:115]
	v_mov_b64_e32 v[140:141], v[118:119]
	v_mov_b64_e32 v[132:133], v[122:123]
	v_mov_b64_e32 v[144:145], v[126:127]
	s_cbranch_vccnz .LBB0_480
	s_waitcnt vmcnt(2)
	v_mov_b64_e32 v[130:131], v[230:231]
	v_mov_b64_e32 v[132:133], v[232:233]
	v_mov_b64_e32 v[134:135], v[234:235]
	v_mov_b64_e32 v[136:137], v[236:237]
	v_mov_b64_e32 v[138:139], v[238:239]
	v_mov_b64_e32 v[140:141], v[240:241]
	v_mov_b64_e32 v[152:153], v[242:243]
	v_mov_b64_e32 v[154:155], v[244:245]
	v_lshl_add_u64 v[246:247], v[246:247], 0, s[98:99]
	v_lshl_add_u64 v[248:249], v[248:249], 0, s[98:99]
	global_load_dwordx4 v[230:233], v[246:247], off
	global_load_dwordx4 v[234:237], v[246:247], off offset:16
	global_load_dwordx4 v[238:241], v[248:249], off
	global_load_dwordx4 v[242:245], v[248:249], off offset:16
	v_pk_mul_f32 v[142:143], v[120:121], v[132:133]
	v_pk_mul_f32 v[144:145], v[118:119], v[130:131]
	v_pk_mul_f32 v[156:157], v[116:117], v[136:137]
	v_pk_mul_f32 v[158:159], v[114:115], v[134:135]
	v_pk_mul_f32 v[160:161], v[128:129], v[132:133]
	v_pk_mul_f32 v[130:131], v[126:127], v[130:131]
	v_pk_mul_f32 v[136:137], v[124:125], v[136:137]
	v_pk_mul_f32 v[162:163], v[122:123], v[134:135]
	v_pk_fma_f32 v[146:147], v[128:129], v[140:141], v[142:143] neg_lo:[0,0,1] neg_hi:[0,0,1]
	v_pk_fma_f32 v[144:145], v[126:127], v[138:139], v[144:145] neg_lo:[0,0,1] neg_hi:[0,0,1]
	v_pk_fma_f32 v[134:135], v[124:125], v[154:155], v[156:157] neg_lo:[0,0,1] neg_hi:[0,0,1]
	v_pk_fma_f32 v[132:133], v[122:123], v[152:153], v[158:159] neg_lo:[0,0,1] neg_hi:[0,0,1]
	v_pk_fma_f32 v[142:143], v[120:121], v[140:141], v[160:161]
	v_pk_fma_f32 v[140:141], v[118:119], v[138:139], v[130:131]
	v_pk_fma_f32 v[138:139], v[116:117], v[154:155], v[136:137]
	v_pk_fma_f32 v[136:137], v[114:115], v[152:153], v[162:163]

; __device__ __forceinline__ u32x4 pack8(const f32x4 a, const f32x4 b) { u32x4 w; w.x = cvt_pk_bf16(a[0], a[1]); w.y = cvt_pk_bf16(a[2], a[3]); w.z = cvt_pk_bf16(b[0], b[1]); w.w = cvt_pk_bf16(b[2], b[3]); return w; }
; #define ROPE_LOAD(C0, C1, S0, S1, r_) do { const int pos_ = (u.pm * BM + ((r_) >> 2) * HALF + wr * 64 + ((r_) & 3) * 16 + fr) & (SEQ - 1); const float* cp_ = cosT + pos_ * 32 + fq * 8; const float* sp_ = sinT + pos_ * 32 + fq * 8; \
;             C0 = *(const f32x4*)cp_; C1 = *(const f32x4*)(cp_ + 4); S0 = *(const f32x4*)sp_; S1 = *(const f32x4*)(sp_ + 4); } while (0)
;     __device__ __forceinline__ void operator()(const f32x4 (&acc)[2][2][4][2], const Unit& u, int wr, int wc, int fr, int fq) const {
;     ...
; #pragma unroll
;         for (int r = 0; r < 8; ++r) { const int ai = r >> 2, m = r & 3; const int row = EPI_ROW; const float rs = rsv[ai][m];
;             f32x4 a0 = acc[ai][0][m][0] * rs + ba0, a1 = acc[ai][0][m][1] * rs + ba1, b0 = acc[ai][1][m][0] * rs + bb0, b1 = acc[ai][1][m][1] * rs + bb1;
;             bf16_t* rp = dst + (size_t)row * pitch;
;             if (mode == 1) { *(u32x4*)(rp + c0) = pack8(a0 * b0, a1 * b1); }
;             else if (mode == 3) {
; #pragma unroll
;                 for (int i = 0; i < 4; ++i) {
;                     const float ea0 = __expf(-a0[i]), ea1 = __expf(-a1[i]), eb0 = __expf(-b0[i]), eb1 = __expf(-b1[i]);
;                     a0[i] = (1.f + eb0) * __builtin_amdgcn_rcpf(1.f + ea0); a1[i] = (1.f + eb1) * __builtin_amdgcn_rcpf(1.f + ea1); b0[i] = __builtin_amdgcn_rcpf(1.f + eb0); b1[i] = __builtin_amdgcn_rcpf(1.f + eb1); }
;                 { const size_t po = (size_t)(row >> 1) * (2 * DM) + ((pn - 18) * 4 + wc) * 64 + (row & 1) * 32 + fq * 8;
;                   *(u32x4*)(SZC + po) = pack8(a0, a1); *(u32x4*)(SZA + po) = pack8(b0, b1); } }
;             else {
;                 if (mode == 2) { f32x4 cA, cB, sA, sB; ROPE_LOAD(cA, cB, sA, sB, r); const f32x4 x0 = a0, x1 = a1, y0 = b0, y1 = b1;
;                     a0 = x0 * cA - y0 * sA; a1 = x1 * cB - y1 * sB; b0 = y0 * cA + x0 * sA; b1 = y1 * cB + x1 * sB; }
.LBB0_490:
	s_or_b32 s28, s31, 32
	v_add_u32_e32 v132, s28, v175
	v_pk_fma_f32 v[112:113], v[112:113], v[202:203], v[56:57] op_sel_hi:[1,0,1]
	v_pk_fma_f32 v[110:111], v[110:111], v[202:203], v[54:55] op_sel_hi:[1,0,1]
	v_pk_fma_f32 v[108:109], v[108:109], v[202:203], v[52:53] op_sel_hi:[1,0,1]
	v_pk_fma_f32 v[106:107], v[106:107], v[202:203], v[50:51] op_sel_hi:[1,0,1]
	v_pk_fma_f32 v[104:105], v[104:105], v[202:203], v[48:49] op_sel_hi:[1,0,1]
	v_pk_fma_f32 v[102:103], v[102:103], v[202:203], v[46:47] op_sel_hi:[1,0,1]
	v_pk_fma_f32 v[100:101], v[100:101], v[202:203], v[44:45] op_sel_hi:[1,0,1]
	v_pk_fma_f32 v[98:99], v[98:99], v[202:203], v[42:43] op_sel_hi:[1,0,1]
	s_and_b64 vcc, exec, s[10:11]
	s_mov_b64 s[56:57], -1
	s_cbranch_vccnz .LBB0_502
	s_and_b64 vcc, exec, s[8:9]
	s_cbranch_vccnz .LBB0_499
	v_mov_b64_e32 v[122:123], v[100:101]
	v_mov_b64_e32 v[126:127], v[104:105]
	v_mov_b64_e32 v[118:119], v[108:109]
	v_mov_b64_e32 v[130:131], v[112:113]
	s_andn2_b64 vcc, exec, s[54:55]
	v_mov_b64_e32 v[120:121], v[98:99]
	v_mov_b64_e32 v[124:125], v[102:103]
	v_mov_b64_e32 v[116:117], v[106:107]
	v_mov_b64_e32 v[128:129], v[110:111]
	s_cbranch_vccnz .LBB0_494
	s_waitcnt vmcnt(2)
	v_mov_b64_e32 v[114:115], v[230:231]
	v_mov_b64_e32 v[116:117], v[232:233]
	v_mov_b64_e32 v[118:119], v[234:235]
	v_mov_b64_e32 v[120:121], v[236:237]
	v_mov_b64_e32 v[122:123], v[238:239]
	v_mov_b64_e32 v[124:125], v[240:241]
	v_mov_b64_e32 v[134:135], v[242:243]
	v_mov_b64_e32 v[136:137], v[244:245]
	v_lshl_add_u64 v[246:247], v[246:247], 0, s[98:99]
	v_lshl_add_u64 v[248:249], v[248:249], 0, s[98:99]
	global_load_dwordx4 v[230:233], v[246:247], off
	global_load_dwordx4 v[234:237], v[246:247], off offset:16
	global_load_dwordx4 v[238:241], v[248:249], off
	global_load_dwordx4 v[242:245], v[248:249], off offset:16
	v_pk_mul_f32 v[126:127], v[104:105], v[116:117]
	v_pk_mul_f32 v[128:129], v[102:103], v[114:115]
	v_pk_mul_f32 v[138:139], v[100:101], v[120:121]
	v_pk_mul_f32 v[140:141], v[98:99], v[118:119]
	v_pk_mul_f32 v[142:143], v[112:113], v[116:117]
	v_pk_mul_f32 v[114:115], v[110:111], v[114:115]
	v_pk_mul_f32 v[120:121], v[108:109], v[120:121]
	v_pk_mul_f32 v[144:145], v[106:107], v[118:119]
	v_pk_fma_f32 v[130:131], v[112:113], v[124:125], v[126:127] neg_lo:[0,0,1] neg_hi:[0,0,1]
	v_pk_fma_f32 v[128:129], v[110:111], v[122:123], v[128:129] neg_lo:[0,0,1] neg_hi:[0,0,1]
	v_pk_fma_f32 v[118:119], v[108:109], v[136:137], v[138:139] neg_lo:[0,0,1] neg_hi:[0,0,1]
	v_pk_fma_f32 v[116:117], v[106:107], v[134:135], v[140:141] neg_lo:[0,0,1] neg_hi:[0,0,1]
	v_pk_fma_f32 v[126:127], v[104:105], v[124:125], v[142:143]
	v_pk_fma_f32 v[124:125], v[102:103], v[122:123], v[114:115]
	v_pk_fma_f32 v[122:123], v[100:101], v[136:137], v[120:121]
	v_pk_fma_f32 v[120:121], v[98:99], v[134:135], v[144:145]

; __device__ __forceinline__ u32x4 pack8(const f32x4 a, const f32x4 b) { u32x4 w; w.x = cvt_pk_bf16(a[0], a[1]); w.y = cvt_pk_bf16(a[2], a[3]); w.z = cvt_pk_bf16(b[0], b[1]); w.w = cvt_pk_bf16(b[2], b[3]); return w; }
; #define ROPE_LOAD(C0, C1, S0, S1, r_) do { const int pos_ = (u.pm * BM + ((r_) >> 2) * HALF + wr * 64 + ((r_) & 3) * 16 + fr) & (SEQ - 1); const float* cp_ = cosT + pos_ * 32 + fq * 8; const float* sp_ = sinT + pos_ * 32 + fq * 8; \
;             C0 = *(const f32x4*)cp_; C1 = *(const f32x4*)(cp_ + 4); S0 = *(const f32x4*)sp_; S1 = *(const f32x4*)(sp_ + 4); } while (0)
;     __device__ __forceinline__ void operator()(const f32x4 (&acc)[2][2][4][2], const Unit& u, int wr, int wc, int fr, int fq) const {
;     ...
; #pragma unroll
;         for (int r = 0; r < 8; ++r) { const int ai = r >> 2, m = r & 3; const int row = EPI_ROW; const float rs = rsv[ai][m];
;             f32x4 a0 = acc[ai][0][m][0] * rs + ba0, a1 = acc[ai][0][m][1] * rs + ba1, b0 = acc[ai][1][m][0] * rs + bb0, b1 = acc[ai][1][m][1] * rs + bb1;
;             bf16_t* rp = dst + (size_t)row * pitch;
;             if (mode == 1) { *(u32x4*)(rp + c0) = pack8(a0 * b0, a1 * b1); }
;             else if (mode == 3) {
; #pragma unroll
;                 for (int i = 0; i < 4; ++i) {
;                     const float ea0 = __expf(-a0[i]), ea1 = __expf(-a1[i]), eb0 = __expf(-b0[i]), eb1 = __expf(-b1[i]);
;                     a0[i] = (1.f + eb0) * __builtin_amdgcn_rcpf(1.f + ea0); a1[i] = (1.f + eb1) * __builtin_amdgcn_rcpf(1.f + ea1); b0[i] = __builtin_amdgcn_rcpf(1.f + eb0); b1[i] = __builtin_amdgcn_rcpf(1.f + eb1); }
;                 { const size_t po = (size_t)(row >> 1) * (2 * DM) + ((pn - 18) * 4 + wc) * 64 + (row & 1) * 32 + fq * 8;
;                   *(u32x4*)(SZC + po) = pack8(a0, a1); *(u32x4*)(SZA + po) = pack8(b0, b1); } }
;             else {
;                 if (mode == 2) { f32x4 cA, cB, sA, sB; ROPE_LOAD(cA, cB, sA, sB, r); const f32x4 x0 = a0, x1 = a1, y0 = b0, y1 = b1;
;                     a0 = x0 * cA - y0 * sA; a1 = x1 * cB - y1 * sB; b0 = y0 * cA + x0 * sA; b1 = y1 * cB + x1 * sB; }
.LBB0_504:
	s_or_b32 s28, s31, 48
	v_add_u32_e32 v116, s28, v175
	v_pk_fma_f32 v[96:97], v[96:97], v[200:201], v[56:57] op_sel_hi:[1,0,1]
	v_pk_fma_f32 v[94:95], v[94:95], v[200:201], v[54:55] op_sel_hi:[1,0,1]
	v_pk_fma_f32 v[92:93], v[92:93], v[200:201], v[52:53] op_sel_hi:[1,0,1]
	v_pk_fma_f32 v[90:91], v[90:91], v[200:201], v[50:51] op_sel_hi:[1,0,1]
	v_pk_fma_f32 v[88:89], v[88:89], v[200:201], v[48:49] op_sel_hi:[1,0,1]
	v_pk_fma_f32 v[86:87], v[86:87], v[200:201], v[46:47] op_sel_hi:[1,0,1]
	v_pk_fma_f32 v[84:85], v[84:85], v[200:201], v[44:45] op_sel_hi:[1,0,1]
	v_pk_fma_f32 v[82:83], v[82:83], v[200:201], v[42:43] op_sel_hi:[1,0,1]
	s_and_b64 vcc, exec, s[10:11]
	s_mov_b64 s[56:57], -1
	s_cbranch_vccnz .LBB0_516
	s_and_b64 vcc, exec, s[8:9]
	s_cbranch_vccnz .LBB0_513
	v_mov_b64_e32 v[106:107], v[84:85]
	v_mov_b64_e32 v[110:111], v[88:89]
	v_mov_b64_e32 v[102:103], v[92:93]
	v_mov_b64_e32 v[114:115], v[96:97]
	s_andn2_b64 vcc, exec, s[54:55]
	v_mov_b64_e32 v[104:105], v[82:83]
	v_mov_b64_e32 v[108:109], v[86:87]
	v_mov_b64_e32 v[100:101], v[90:91]
	v_mov_b64_e32 v[112:113], v[94:95]
	s_cbranch_vccnz .LBB0_508
	s_waitcnt vmcnt(2)
	v_mov_b64_e32 v[98:99], v[230:231]
	v_mov_b64_e32 v[100:101], v[232:233]
	v_mov_b64_e32 v[102:103], v[234:235]
	v_mov_b64_e32 v[104:105], v[236:237]
	v_mov_b64_e32 v[106:107], v[238:239]
	v_mov_b64_e32 v[108:109], v[240:241]
	v_mov_b64_e32 v[118:119], v[242:243]
	v_mov_b64_e32 v[120:121], v[244:245]
	v_lshl_add_u64 v[246:247], v[246:247], 0, s[100:101]
	v_lshl_add_u64 v[248:249], v[248:249], 0, s[100:101]
	global_load_dwordx4 v[230:233], v[246:247], off
	global_load_dwordx4 v[234:237], v[246:247], off offset:16
	global_load_dwordx4 v[238:241], v[248:249], off
	global_load_dwordx4 v[242:245], v[248:249], off offset:16
	v_pk_mul_f32 v[110:111], v[88:89], v[100:101]
	v_pk_mul_f32 v[112:113], v[86:87], v[98:99]
	v_pk_mul_f32 v[122:123], v[84:85], v[104:105]
	v_pk_mul_f32 v[124:125], v[82:83], v[102:103]
	v_pk_mul_f32 v[126:127], v[96:97], v[100:101]
	v_pk_mul_f32 v[98:99], v[94:95], v[98:99]
	v_pk_mul_f32 v[104:105], v[92:93], v[104:105]
	v_pk_mul_f32 v[128:129], v[90:91], v[102:103]
	v_pk_fma_f32 v[114:115], v[96:97], v[108:109], v[110:111] neg_lo:[0,0,1] neg_hi:[0,0,1]
	v_pk_fma_f32 v[112:113], v[94:95], v[106:107], v[112:113] neg_lo:[0,0,1] neg_hi:[0,0,1]
	v_pk_fma_f32 v[102:103], v[92:93], v[120:121], v[122:123] neg_lo:[0,0,1] neg_hi:[0,0,1]
	v_pk_fma_f32 v[100:101], v[90:91], v[118:119], v[124:125] neg_lo:[0,0,1] neg_hi:[0,0,1]
	v_pk_fma_f32 v[110:111], v[88:89], v[108:109], v[126:127]
	v_pk_fma_f32 v[108:109], v[86:87], v[106:107], v[98:99]
	v_pk_fma_f32 v[106:107], v[84:85], v[120:121], v[104:105]
	v_pk_fma_f32 v[104:105], v[82:83], v[118:119], v[128:129]

; __device__ __forceinline__ u32x4 pack8(const f32x4 a, const f32x4 b) { u32x4 w; w.x = cvt_pk_bf16(a[0], a[1]); w.y = cvt_pk_bf16(a[2], a[3]); w.z = cvt_pk_bf16(b[0], b[1]); w.w = cvt_pk_bf16(b[2], b[3]); return w; }
; #define ROPE_LOAD(C0, C1, S0, S1, r_) do { const int pos_ = (u.pm * BM + ((r_) >> 2) * HALF + wr * 64 + ((r_) & 3) * 16 + fr) & (SEQ - 1); const float* cp_ = cosT + pos_ * 32 + fq * 8; const float* sp_ = sinT + pos_ * 32 + fq * 8; \
;             C0 = *(const f32x4*)cp_; C1 = *(const f32x4*)(cp_ + 4); S0 = *(const f32x4*)sp_; S1 = *(const f32x4*)(sp_ + 4); } while (0)
;     __device__ __forceinline__ void operator()(const f32x4 (&acc)[2][2][4][2], const Unit& u, int wr, int wc, int fr, int fq) const {
;     ...
; #pragma unroll
;         for (int r = 0; r < 8; ++r) { const int ai = r >> 2, m = r & 3; const int row = EPI_ROW; const float rs = rsv[ai][m];
;             f32x4 a0 = acc[ai][0][m][0] * rs + ba0, a1 = acc[ai][0][m][1] * rs + ba1, b0 = acc[ai][1][m][0] * rs + bb0, b1 = acc[ai][1][m][1] * rs + bb1;
;             bf16_t* rp = dst + (size_t)row * pitch;
;             if (mode == 1) { *(u32x4*)(rp + c0) = pack8(a0 * b0, a1 * b1); }
;             else if (mode == 3) {
; #pragma unroll
;                 for (int i = 0; i < 4; ++i) {
;                     const float ea0 = __expf(-a0[i]), ea1 = __expf(-a1[i]), eb0 = __expf(-b0[i]), eb1 = __expf(-b1[i]);
;                     a0[i] = (1.f + eb0) * __builtin_amdgcn_rcpf(1.f + ea0); a1[i] = (1.f + eb1) * __builtin_amdgcn_rcpf(1.f + ea1); b0[i] = __builtin_amdgcn_rcpf(1.f + eb0); b1[i] = __builtin_amdgcn_rcpf(1.f + eb1); }
;                 { const size_t po = (size_t)(row >> 1) * (2 * DM) + ((pn - 18) * 4 + wc) * 64 + (row & 1) * 32 + fq * 8;
;                   *(u32x4*)(SZC + po) = pack8(a0, a1); *(u32x4*)(SZA + po) = pack8(b0, b1); } }
;             else {
;                 if (mode == 2) { f32x4 cA, cB, sA, sB; ROPE_LOAD(cA, cB, sA, sB, r); const f32x4 x0 = a0, x1 = a1, y0 = b0, y1 = b1;
;                     a0 = x0 * cA - y0 * sA; a1 = x1 * cB - y1 * sB; b0 = y0 * cA + x0 * sA; b1 = y1 * cB + x1 * sB; }
.LBB0_518:
	s_addk_i32 s31, 0x80
	v_add_u32_e32 v100, s31, v175
	v_pk_fma_f32 v[80:81], v[80:81], v[198:199], v[56:57] op_sel_hi:[1,0,1]
	v_pk_fma_f32 v[78:79], v[78:79], v[198:199], v[54:55] op_sel_hi:[1,0,1]
	v_pk_fma_f32 v[76:77], v[76:77], v[198:199], v[52:53] op_sel_hi:[1,0,1]
	v_pk_fma_f32 v[74:75], v[74:75], v[198:199], v[50:51] op_sel_hi:[1,0,1]
	v_pk_fma_f32 v[72:73], v[72:73], v[198:199], v[48:49] op_sel_hi:[1,0,1]
	v_pk_fma_f32 v[70:71], v[70:71], v[198:199], v[46:47] op_sel_hi:[1,0,1]
	v_pk_fma_f32 v[68:69], v[68:69], v[198:199], v[44:45] op_sel_hi:[1,0,1]
	v_pk_fma_f32 v[66:67], v[66:67], v[198:199], v[42:43] op_sel_hi:[1,0,1]
	s_and_b64 vcc, exec, s[10:11]
	s_mov_b64 s[56:57], -1
	s_cbranch_vccnz .LBB0_530
	s_and_b64 vcc, exec, s[8:9]
	s_cbranch_vccnz .LBB0_527
	v_mov_b64_e32 v[90:91], v[68:69]
	v_mov_b64_e32 v[94:95], v[72:73]
	v_mov_b64_e32 v[86:87], v[76:77]
	v_mov_b64_e32 v[98:99], v[80:81]
	s_andn2_b64 vcc, exec, s[54:55]
	v_mov_b64_e32 v[88:89], v[66:67]
	v_mov_b64_e32 v[92:93], v[70:71]
	v_mov_b64_e32 v[84:85], v[74:75]
	v_mov_b64_e32 v[96:97], v[78:79]
	s_cbranch_vccnz .LBB0_522
	s_waitcnt vmcnt(2)
	v_mov_b64_e32 v[82:83], v[230:231]
	v_mov_b64_e32 v[84:85], v[232:233]
	v_mov_b64_e32 v[86:87], v[234:235]
	v_mov_b64_e32 v[88:89], v[236:237]
	v_mov_b64_e32 v[90:91], v[238:239]
	v_mov_b64_e32 v[92:93], v[240:241]
	v_mov_b64_e32 v[102:103], v[242:243]
	v_mov_b64_e32 v[104:105], v[244:245]
	v_lshl_add_u64 v[246:247], v[246:247], 0, s[98:99]
	v_lshl_add_u64 v[248:249], v[248:249], 0, s[98:99]
	global_load_dwordx4 v[230:233], v[246:247], off
	global_load_dwordx4 v[234:237], v[246:247], off offset:16
	global_load_dwordx4 v[238:241], v[248:249], off
	global_load_dwordx4 v[242:245], v[248:249], off offset:16
	v_pk_mul_f32 v[94:95], v[72:73], v[84:85]
	v_pk_mul_f32 v[96:97], v[70:71], v[82:83]
	v_pk_mul_f32 v[106:107], v[68:69], v[88:89]
	v_pk_mul_f32 v[108:109], v[66:67], v[86:87]
	v_pk_mul_f32 v[110:111], v[80:81], v[84:85]
	v_pk_mul_f32 v[82:83], v[78:79], v[82:83]
	v_pk_mul_f32 v[88:89], v[76:77], v[88:89]
	v_pk_mul_f32 v[112:113], v[74:75], v[86:87]
	v_pk_fma_f32 v[98:99], v[80:81], v[92:93], v[94:95] neg_lo:[0,0,1] neg_hi:[0,0,1]
	v_pk_fma_f32 v[96:97], v[78:79], v[90:91], v[96:97] neg_lo:[0,0,1] neg_hi:[0,0,1]
	v_pk_fma_f32 v[86:87], v[76:77], v[104:105], v[106:107] neg_lo:[0,0,1] neg_hi:[0,0,1]
	v_pk_fma_f32 v[84:85], v[74:75], v[102:103], v[108:109] neg_lo:[0,0,1] neg_hi:[0,0,1]
	v_pk_fma_f32 v[94:95], v[72:73], v[92:93], v[110:111]
	v_pk_fma_f32 v[92:93], v[70:71], v[90:91], v[82:83]
	v_pk_fma_f32 v[90:91], v[68:69], v[104:105], v[88:89]
	v_pk_fma_f32 v[88:89], v[66:67], v[102:103], v[112:113]

; __device__ __forceinline__ u32x4 pack8(const f32x4 a, const f32x4 b) { u32x4 w; w.x = cvt_pk_bf16(a[0], a[1]); w.y = cvt_pk_bf16(a[2], a[3]); w.z = cvt_pk_bf16(b[0], b[1]); w.w = cvt_pk_bf16(b[2], b[3]); return w; }
; #define ROPE_LOAD(C0, C1, S0, S1, r_) do { const int pos_ = (u.pm * BM + ((r_) >> 2) * HALF + wr * 64 + ((r_) & 3) * 16 + fr) & (SEQ - 1); const float* cp_ = cosT + pos_ * 32 + fq * 8; const float* sp_ = sinT + pos_ * 32 + fq * 8; \
;             C0 = *(const f32x4*)cp_; C1 = *(const f32x4*)(cp_ + 4); S0 = *(const f32x4*)sp_; S1 = *(const f32x4*)(sp_ + 4); } while (0)
;     __device__ __forceinline__ void operator()(const f32x4 (&acc)[2][2][4][2], const Unit& u, int wr, int wc, int fr, int fq) const {
;     ...
;         for (int r = 0; r < 8; ++r) { const int ai = r >> 2, m = r & 3; const int row = EPI_ROW; const float rs = rsv[ai][m];
;             f32x4 a0 = acc[ai][0][m][0] * rs + ba0, a1 = acc[ai][0][m][1] * rs + ba1, b0 = acc[ai][1][m][0] * rs + bb0, b1 = acc[ai][1][m][1] * rs + bb1;
;             bf16_t* rp = dst + (size_t)row * pitch;
;             if (mode == 1) { *(u32x4*)(rp + c0) = pack8(a0 * b0, a1 * b1); }
;             else if (mode == 3) {
; #pragma unroll
;                 for (int i = 0; i < 4; ++i) {
;                     const float ea0 = __expf(-a0[i]), ea1 = __expf(-a1[i]), eb0 = __expf(-b0[i]), eb1 = __expf(-b1[i]);
;                     a0[i] = (1.f + eb0) * __builtin_amdgcn_rcpf(1.f + ea0); a1[i] = (1.f + eb1) * __builtin_amdgcn_rcpf(1.f + ea1); b0[i] = __builtin_amdgcn_rcpf(1.f + eb0); b1[i] = __builtin_amdgcn_rcpf(1.f + eb1); }
;                 { const size_t po = (size_t)(row >> 1) * (2 * DM) + ((pn - 18) * 4 + wc) * 64 + (row & 1) * 32 + fq * 8;
;                   *(u32x4*)(SZC + po) = pack8(a0, a1); *(u32x4*)(SZA + po) = pack8(b0, b1); } }
;             else {
;                 if (mode == 2) { f32x4 cA, cB, sA, sB; ROPE_LOAD(cA, cB, sA, sB, r); const f32x4 x0 = a0, x1 = a1, y0 = b0, y1 = b1;
;                     a0 = x0 * cA - y0 * sA; a1 = x1 * cB - y1 * sB; b0 = y0 * cA + x0 * sA; b1 = y1 * cB + x1 * sB; }
.LBB0_532:
	s_or_b32 s28, s31, 16
	v_add_u32_e32 v84, s28, v175
	v_pk_fma_f32 v[64:65], v[64:65], v[196:197], v[56:57] op_sel_hi:[1,0,1]
	v_pk_fma_f32 v[62:63], v[62:63], v[196:197], v[54:55] op_sel_hi:[1,0,1]
	v_pk_fma_f32 v[60:61], v[60:61], v[196:197], v[52:53] op_sel_hi:[1,0,1]
	v_pk_fma_f32 v[58:59], v[58:59], v[196:197], v[50:51] op_sel_hi:[1,0,1]
	v_pk_fma_f32 v[40:41], v[40:41], v[196:197], v[48:49] op_sel_hi:[1,0,1]
	v_pk_fma_f32 v[38:39], v[38:39], v[196:197], v[46:47] op_sel_hi:[1,0,1]
	v_pk_fma_f32 v[36:37], v[36:37], v[196:197], v[44:45] op_sel_hi:[1,0,1]
	v_pk_fma_f32 v[34:35], v[34:35], v[196:197], v[42:43] op_sel_hi:[1,0,1]
	s_and_b64 vcc, exec, s[10:11]
	s_mov_b64 s[56:57], -1
	s_cbranch_vccnz .LBB0_544
	s_and_b64 vcc, exec, s[8:9]
	s_cbranch_vccnz .LBB0_541
	v_mov_b64_e32 v[74:75], v[36:37]
	v_mov_b64_e32 v[78:79], v[40:41]
	v_mov_b64_e32 v[70:71], v[60:61]
	v_mov_b64_e32 v[82:83], v[64:65]
	s_andn2_b64 vcc, exec, s[54:55]
	v_mov_b64_e32 v[72:73], v[34:35]
	v_mov_b64_e32 v[76:77], v[38:39]
	v_mov_b64_e32 v[68:69], v[58:59]
	v_mov_b64_e32 v[80:81], v[62:63]
	s_cbranch_vccnz .LBB0_536
	s_waitcnt vmcnt(2)
	v_mov_b64_e32 v[66:67], v[230:231]
	v_mov_b64_e32 v[68:69], v[232:233]
	v_mov_b64_e32 v[70:71], v[234:235]
	v_mov_b64_e32 v[72:73], v[236:237]
	v_mov_b64_e32 v[74:75], v[238:239]
	v_mov_b64_e32 v[76:77], v[240:241]
	v_mov_b64_e32 v[86:87], v[242:243]
	v_mov_b64_e32 v[88:89], v[244:245]
	v_lshl_add_u64 v[246:247], v[246:247], 0, s[98:99]
	v_lshl_add_u64 v[248:249], v[248:249], 0, s[98:99]
	global_load_dwordx4 v[230:233], v[246:247], off
	global_load_dwordx4 v[234:237], v[246:247], off offset:16
	global_load_dwordx4 v[238:241], v[248:249], off
	global_load_dwordx4 v[242:245], v[248:249], off offset:16
	v_pk_mul_f32 v[78:79], v[40:41], v[68:69]
	v_pk_mul_f32 v[80:81], v[38:39], v[66:67]
	v_pk_mul_f32 v[90:91], v[36:37], v[72:73]
	v_pk_mul_f32 v[92:93], v[34:35], v[70:71]
	v_pk_mul_f32 v[94:95], v[64:65], v[68:69]
	v_pk_mul_f32 v[66:67], v[62:63], v[66:67]
	v_pk_mul_f32 v[72:73], v[60:61], v[72:73]
	v_pk_mul_f32 v[96:97], v[58:59], v[70:71]
	v_pk_fma_f32 v[82:83], v[64:65], v[76:77], v[78:79] neg_lo:[0,0,1] neg_hi:[0,0,1]
	v_pk_fma_f32 v[80:81], v[62:63], v[74:75], v[80:81] neg_lo:[0,0,1] neg_hi:[0,0,1]
	v_pk_fma_f32 v[70:71], v[60:61], v[88:89], v[90:91] neg_lo:[0,0,1] neg_hi:[0,0,1]
	v_pk_fma_f32 v[68:69], v[58:59], v[86:87], v[92:93] neg_lo:[0,0,1] neg_hi:[0,0,1]
	v_pk_fma_f32 v[78:79], v[40:41], v[76:77], v[94:95]
	v_pk_fma_f32 v[76:77], v[38:39], v[74:75], v[66:67]
	v_pk_fma_f32 v[74:75], v[36:37], v[88:89], v[72:73]
	v_pk_fma_f32 v[72:73], v[34:35], v[86:87], v[96:97]

; __device__ __forceinline__ u32x4 pack8(const f32x4 a, const f32x4 b) { u32x4 w; w.x = cvt_pk_bf16(a[0], a[1]); w.y = cvt_pk_bf16(a[2], a[3]); w.z = cvt_pk_bf16(b[0], b[1]); w.w = cvt_pk_bf16(b[2], b[3]); return w; }
; #define ROPE_LOAD(C0, C1, S0, S1, r_) do { const int pos_ = (u.pm * BM + ((r_) >> 2) * HALF + wr * 64 + ((r_) & 3) * 16 + fr) & (SEQ - 1); const float* cp_ = cosT + pos_ * 32 + fq * 8; const float* sp_ = sinT + pos_ * 32 + fq * 8; \
;             C0 = *(const f32x4*)cp_; C1 = *(const f32x4*)(cp_ + 4); S0 = *(const f32x4*)sp_; S1 = *(const f32x4*)(sp_ + 4); } while (0)
;     __device__ __forceinline__ void operator()(const f32x4 (&acc)[2][2][4][2], const Unit& u, int wr, int wc, int fr, int fq) const {
;     ...
;         for (int r = 0; r < 8; ++r) { const int ai = r >> 2, m = r & 3; const int row = EPI_ROW; const float rs = rsv[ai][m];
;             f32x4 a0 = acc[ai][0][m][0] * rs + ba0, a1 = acc[ai][0][m][1] * rs + ba1, b0 = acc[ai][1][m][0] * rs + bb0, b1 = acc[ai][1][m][1] * rs + bb1;
;             bf16_t* rp = dst + (size_t)row * pitch;
;             if (mode == 1) { *(u32x4*)(rp + c0) = pack8(a0 * b0, a1 * b1); }
;             else if (mode == 3) {
; #pragma unroll
;                 for (int i = 0; i < 4; ++i) {
;                     const float ea0 = __expf(-a0[i]), ea1 = __expf(-a1[i]), eb0 = __expf(-b0[i]), eb1 = __expf(-b1[i]);
;                     a0[i] = (1.f + eb0) * __builtin_amdgcn_rcpf(1.f + ea0); a1[i] = (1.f + eb1) * __builtin_amdgcn_rcpf(1.f + ea1); b0[i] = __builtin_amdgcn_rcpf(1.f + eb0); b1[i] = __builtin_amdgcn_rcpf(1.f + eb1); }
;                 { const size_t po = (size_t)(row >> 1) * (2 * DM) + ((pn - 18) * 4 + wc) * 64 + (row & 1) * 32 + fq * 8;
;                   *(u32x4*)(SZC + po) = pack8(a0, a1); *(u32x4*)(SZA + po) = pack8(b0, b1); } }
;             else {
;                 if (mode == 2) { f32x4 cA, cB, sA, sB; ROPE_LOAD(cA, cB, sA, sB, r); const f32x4 x0 = a0, x1 = a1, y0 = b0, y1 = b1;
;                     a0 = x0 * cA - y0 * sA; a1 = x1 * cB - y1 * sB; b0 = y0 * cA + x0 * sA; b1 = y1 * cB + x1 * sB; }
.LBB0_546:
	s_or_b32 s28, s31, 32
	v_add_u32_e32 v66, s28, v175
	v_pk_fma_f32 v[32:33], v[32:33], v[176:177], v[56:57] op_sel_hi:[1,0,1]
	v_pk_fma_f32 v[30:31], v[30:31], v[176:177], v[54:55] op_sel_hi:[1,0,1]
	v_pk_fma_f32 v[28:29], v[28:29], v[176:177], v[52:53] op_sel_hi:[1,0,1]
	v_pk_fma_f32 v[26:27], v[26:27], v[176:177], v[50:51] op_sel_hi:[1,0,1]
	v_pk_fma_f32 v[24:25], v[24:25], v[176:177], v[48:49] op_sel_hi:[1,0,1]
	v_pk_fma_f32 v[22:23], v[22:23], v[176:177], v[46:47] op_sel_hi:[1,0,1]
	v_pk_fma_f32 v[20:21], v[20:21], v[176:177], v[44:45] op_sel_hi:[1,0,1]
	v_pk_fma_f32 v[18:19], v[18:19], v[176:177], v[42:43] op_sel_hi:[1,0,1]
	s_and_b64 vcc, exec, s[10:11]
	s_mov_b64 s[56:57], -1
	s_cbranch_vccnz .LBB0_558
	s_and_b64 vcc, exec, s[8:9]
	s_cbranch_vccnz .LBB0_555
	v_mov_b64_e32 v[60:61], v[20:21]
	v_mov_b64_e32 v[40:41], v[24:25]
	v_mov_b64_e32 v[64:65], v[28:29]
	v_mov_b64_e32 v[36:37], v[32:33]
	s_andn2_b64 vcc, exec, s[54:55]
	v_mov_b64_e32 v[58:59], v[18:19]
	v_mov_b64_e32 v[38:39], v[22:23]
	v_mov_b64_e32 v[62:63], v[26:27]
	v_mov_b64_e32 v[34:35], v[30:31]
	s_cbranch_vccnz .LBB0_550
	s_waitcnt vmcnt(2)
	v_mov_b64_e32 v[34:35], v[230:231]
	v_mov_b64_e32 v[36:37], v[232:233]
	v_mov_b64_e32 v[38:39], v[234:235]
	v_mov_b64_e32 v[40:41], v[236:237]
	v_mov_b64_e32 v[58:59], v[238:239]
	v_mov_b64_e32 v[60:61], v[240:241]
	v_mov_b64_e32 v[68:69], v[242:243]
	v_mov_b64_e32 v[70:71], v[244:245]
	v_lshl_add_u64 v[246:247], v[246:247], 0, s[98:99]
	v_lshl_add_u64 v[248:249], v[248:249], 0, s[98:99]
	global_load_dwordx4 v[230:233], v[246:247], off
	global_load_dwordx4 v[234:237], v[246:247], off offset:16
	global_load_dwordx4 v[238:241], v[248:249], off
	global_load_dwordx4 v[242:245], v[248:249], off offset:16
	v_pk_mul_f32 v[62:63], v[24:25], v[36:37]
	v_pk_mul_f32 v[64:65], v[22:23], v[34:35]
	v_pk_mul_f32 v[72:73], v[20:21], v[40:41]
	v_pk_mul_f32 v[74:75], v[18:19], v[38:39]
	v_pk_mul_f32 v[76:77], v[32:33], v[36:37]
	v_pk_mul_f32 v[78:79], v[30:31], v[34:35]
	v_pk_mul_f32 v[80:81], v[28:29], v[40:41]
	v_pk_mul_f32 v[82:83], v[26:27], v[38:39]
	v_pk_fma_f32 v[36:37], v[32:33], v[60:61], v[62:63] neg_lo:[0,0,1] neg_hi:[0,0,1]
	v_pk_fma_f32 v[34:35], v[30:31], v[58:59], v[64:65] neg_lo:[0,0,1] neg_hi:[0,0,1]
	v_pk_fma_f32 v[64:65], v[28:29], v[70:71], v[72:73] neg_lo:[0,0,1] neg_hi:[0,0,1]
	v_pk_fma_f32 v[62:63], v[26:27], v[68:69], v[74:75] neg_lo:[0,0,1] neg_hi:[0,0,1]
	v_pk_fma_f32 v[40:41], v[24:25], v[60:61], v[76:77]
	v_pk_fma_f32 v[38:39], v[22:23], v[58:59], v[78:79]
	v_pk_fma_f32 v[60:61], v[20:21], v[70:71], v[80:81]
	v_pk_fma_f32 v[58:59], v[18:19], v[68:69], v[82:83]

; __device__ __forceinline__ u32x4 pack8(const f32x4 a, const f32x4 b) { u32x4 w; w.x = cvt_pk_bf16(a[0], a[1]); w.y = cvt_pk_bf16(a[2], a[3]); w.z = cvt_pk_bf16(b[0], b[1]); w.w = cvt_pk_bf16(b[2], b[3]); return w; }
; #define ROPE_LOAD(C0, C1, S0, S1, r_) do { const int pos_ = (u.pm * BM + ((r_) >> 2) * HALF + wr * 64 + ((r_) & 3) * 16 + fr) & (SEQ - 1); const float* cp_ = cosT + pos_ * 32 + fq * 8; const float* sp_ = sinT + pos_ * 32 + fq * 8; \
;             C0 = *(const f32x4*)cp_; C1 = *(const f32x4*)(cp_ + 4); S0 = *(const f32x4*)sp_; S1 = *(const f32x4*)(sp_ + 4); } while (0)
;     __device__ __forceinline__ void operator()(const f32x4 (&acc)[2][2][4][2], const Unit& u, int wr, int wc, int fr, int fq) const {
;     ...
;         for (int r = 0; r < 8; ++r) { const int ai = r >> 2, m = r & 3; const int row = EPI_ROW; const float rs = rsv[ai][m];
;             f32x4 a0 = acc[ai][0][m][0] * rs + ba0, a1 = acc[ai][0][m][1] * rs + ba1, b0 = acc[ai][1][m][0] * rs + bb0, b1 = acc[ai][1][m][1] * rs + bb1;
;             bf16_t* rp = dst + (size_t)row * pitch;
;             if (mode == 1) { *(u32x4*)(rp + c0) = pack8(a0 * b0, a1 * b1); }
;             else if (mode == 3) {
; #pragma unroll
;                 for (int i = 0; i < 4; ++i) {
;                     const float ea0 = __expf(-a0[i]), ea1 = __expf(-a1[i]), eb0 = __expf(-b0[i]), eb1 = __expf(-b1[i]);
;                     a0[i] = (1.f + eb0) * __builtin_amdgcn_rcpf(1.f + ea0); a1[i] = (1.f + eb1) * __builtin_amdgcn_rcpf(1.f + ea1); b0[i] = __builtin_amdgcn_rcpf(1.f + eb0); b1[i] = __builtin_amdgcn_rcpf(1.f + eb1); }
;                 { const size_t po = (size_t)(row >> 1) * (2 * DM) + ((pn - 18) * 4 + wc) * 64 + (row & 1) * 32 + fq * 8;
;                   *(u32x4*)(SZC + po) = pack8(a0, a1); *(u32x4*)(SZA + po) = pack8(b0, b1); } }
;             else {
;                 if (mode == 2) { f32x4 cA, cB, sA, sB; ROPE_LOAD(cA, cB, sA, sB, r); const f32x4 x0 = a0, x1 = a1, y0 = b0, y1 = b1;
;                     a0 = x0 * cA - y0 * sA; a1 = x1 * cB - y1 * sB; b0 = y0 * cA + x0 * sA; b1 = y1 * cB + x1 * sB; }
.LBB0_563:
	s_and_b64 vcc, exec, s[8:9]
	s_mov_b64 s[8:9], -1
	s_cbranch_vccnz .LBB0_571
	v_mov_b64_e32 v[26:27], v[4:5]
	v_mov_b64_e32 v[30:31], v[8:9]
	v_mov_b64_e32 v[22:23], v[12:13]
	v_mov_b64_e32 v[34:35], v[16:17]
	s_andn2_b64 vcc, exec, s[54:55]
	v_mov_b64_e32 v[24:25], v[2:3]
	v_mov_b64_e32 v[28:29], v[6:7]
	v_mov_b64_e32 v[20:21], v[10:11]
	v_mov_b64_e32 v[32:33], v[14:15]
	s_cbranch_vccnz .LBB0_566
	s_waitcnt vmcnt(2)
	v_mov_b64_e32 v[18:19], v[230:231]
	v_mov_b64_e32 v[20:21], v[232:233]
	v_mov_b64_e32 v[22:23], v[234:235]
	v_mov_b64_e32 v[24:25], v[236:237]
	v_mov_b64_e32 v[26:27], v[238:239]
	v_mov_b64_e32 v[28:29], v[240:241]
	v_mov_b64_e32 v[38:39], v[242:243]
	v_mov_b64_e32 v[40:41], v[244:245]
	v_pk_mul_f32 v[30:31], v[8:9], v[20:21]
	v_pk_mul_f32 v[32:33], v[6:7], v[18:19]
	v_pk_mul_f32 v[42:43], v[4:5], v[24:25]
	v_pk_mul_f32 v[44:45], v[2:3], v[22:23]
	v_pk_mul_f32 v[46:47], v[16:17], v[20:21]
	v_pk_mul_f32 v[18:19], v[14:15], v[18:19]
	v_pk_mul_f32 v[24:25], v[12:13], v[24:25]
	v_pk_mul_f32 v[48:49], v[10:11], v[22:23]
	v_pk_fma_f32 v[34:35], v[16:17], v[28:29], v[30:31] neg_lo:[0,0,1] neg_hi:[0,0,1]
	v_pk_fma_f32 v[32:33], v[14:15], v[26:27], v[32:33] neg_lo:[0,0,1] neg_hi:[0,0,1]
	v_pk_fma_f32 v[22:23], v[12:13], v[40:41], v[42:43] neg_lo:[0,0,1] neg_hi:[0,0,1]
	v_pk_fma_f32 v[20:21], v[10:11], v[38:39], v[44:45] neg_lo:[0,0,1] neg_hi:[0,0,1]
	v_pk_fma_f32 v[30:31], v[8:9], v[28:29], v[46:47]
	v_pk_fma_f32 v[28:29], v[6:7], v[26:27], v[18:19]
	v_pk_fma_f32 v[26:27], v[4:5], v[40:41], v[24:25]
	v_pk_fma_f32 v[24:25], v[2:3], v[38:39], v[48:49]
